# s_setprio 1/0 around the 16-MFMA burst of the GEMM_in and GEMM_out main loops
# baseline (speedup 1.0000x reference)
; DI f32x16 mfma32(bf16x8 a, bf16x8 b, f32x16 c) { return __builtin_amdgcn_mfma_f32_32x32x16_bf16(a, b, c, 0, 0, 0); }
; #define RAW_BARRIER() do { asm volatile("s_waitcnt lgkmcnt(0)" ::: "memory"); __builtin_amdgcn_s_barrier(); } while (0)
; DI void gemm_tile(const Params& p, const GemmJob& j, int mt, int nt, char* smem) {
;     ...
;       const bf16_t* src = j.bblk ? j.Bt + ((size_t)kt * j.bblk + n0 + 16 * ch + rl) * 32 + c8s : j.Bt + (size_t)(n0 + 16 * ch + rl) * j.K + kt * 32 + c8s;
;       __builtin_amdgcn_global_load_lds((gptr_t)src, (lptr_t)(sb + ch * 1024), 16, 0, 0);
;     }
; #pragma unroll
;     for (int q = 0; q < 4; ++q) {
;       const int ch = q * 4 + wid;
;       const bf16_t* src = j.ablk ? j.A + ((size_t)kt * j.ablk + t0 + 16 * ch + rl) * 32 + c8s : j.A + a_rowoff(j, t0 + 16 * ch + rl) + ko + c8s;
;       __builtin_amdgcn_global_load_lds((gptr_t)src, (lptr_t)(sb + 8192 + ch * 1024), 16, 0, 0);
;     }
;   };
;   const int fr = (r >> 2) & 3; const int o0 = (h ^ fr) * 16;
;   __syncthreads();
;   glds(0, 0);
;   if (nk > 1) glds(1, 1);
;   int st = 0, st2 = 2;
;   for (int kt = 0; kt < nk; ++kt) {
;     if (kt + 1 < nk) asm volatile("s_waitcnt vmcnt(6)" ::: "memory"); else asm volatile("s_waitcnt vmcnt(0)" ::: "memory");
;     RAW_BARRIER();
;     if (kt + 2 < nk) glds(kt + 2, st2);
;     const char* sb = smem + st * GSTAGE;
; #pragma unroll
;     for (int ks = 0; ks < 2; ++ks) {
;       const int off = ks ? (o0 ^ 32) : o0;
;       bf16x8 wf[2], xf[4];
; #pragma unroll
;       for (int a = 0; a < 2; ++a) wf[a] = *(const bf16x8*)(sb + (64 * wn + 32 * a + r) * 64 + off);
; #pragma unroll
;       for (int b = 0; b < 4; ++b) xf[b] = *(const bf16x8*)(sb + 8192 + (128 * wt + 32 * b + r) * 64 + off);
; #pragma unroll
;       for (int a = 0; a < 2; ++a)
; #pragma unroll
;         for (int b = 0; b < 4; ++b) acc[a][b] = mfma32(wf[a], xf[b], acc[a][b]);
;     }
;     st = (st == 2) ? 0 : st + 1; st2 = (st2 == 2) ? 0 : st2 + 1;
.LBB0_103:
	s_add_i32 s37, s63, s33
	v_lshl_add_u64 v[232:233], v[232:233], 0, v[0:1]
	s_mov_b32 m0, s37
	v_lshl_add_u64 v[134:135], v[134:135], 0, 64
	global_load_lds_dwordx4 v[232:233], off
	v_lshl_add_u64 v[232:233], v[138:139], 0, s[8:9]
	v_lshl_add_u64 v[234:235], v[232:233], 0, s[92:93]
	s_add_i32 m0, s36, 0x2000
	s_add_i32 s36, s63, s55
	global_load_lds_dwordx4 v[234:235], off
	v_lshl_add_u64 v[234:235], v[140:141], 0, s[8:9]
	s_add_i32 m0, s37, 0x2000
	v_lshl_add_u64 v[136:137], v[136:137], 0, 64
	global_load_lds_dwordx4 v[234:235], off
	v_lshl_add_u64 v[234:235], v[232:233], 0, s[84:85]
	s_add_i32 m0, s36, 0x2000
	s_add_i32 s36, s63, s58
	global_load_lds_dwordx4 v[234:235], off
	v_lshl_add_u64 v[232:233], v[232:233], 0, s[52:53]
	s_add_i32 m0, s36, 0x2000
	s_nop 0
	global_load_lds_dwordx4 v[232:233], off
	s_waitcnt lgkmcnt(0)
	s_setprio 1
	v_mfma_f32_32x32x16_bf16 v[114:129], v[152:155], v[156:159], v[114:129]
	v_add_u32_e32 v142, s100, v150
	s_add_i32 s36, s11, 1
	s_cmp_lg_u32 s11, 2
	s_cselect_b32 s11, s36, 0
	s_add_i32 s36, s70, 1
	s_cmp_lg_u32 s70, 2
	s_cselect_b32 s70, s36, 0
	v_mfma_f32_32x32x16_bf16 v[82:97], v[152:155], v[160:163], v[82:97]
	s_add_u32 s8, s8, 0x200000
	s_addc_u32 s9, s9, 0
	s_add_i32 s62, s62, 1
	s_cmp_eq_u32 s8, 0x3c00000
	v_mfma_f32_32x32x16_bf16 v[50:65], v[152:155], v[180:183], v[50:65]
	v_mfma_f32_32x32x16_bf16 v[18:33], v[152:155], v[184:187], v[18:33]
	ds_read_b128 v[152:155], v143 offset:2048
	v_add_u32_e32 v143, v142, v149
	v_add_u32_e32 v142, v142, v148
	s_waitcnt lgkmcnt(0)
	v_mfma_f32_32x32x16_bf16 v[98:113], v[152:155], v[156:159], v[98:113]
	ds_read_b128 v[156:159], v142 offset:8192
	v_mfma_f32_32x32x16_bf16 v[66:81], v[152:155], v[160:163], v[66:81]
	ds_read_b128 v[160:163], v142 offset:10240
	v_mfma_f32_32x32x16_bf16 v[34:49], v[152:155], v[180:183], v[34:49]
	ds_read_b128 v[180:183], v142 offset:12288
	v_mfma_f32_32x32x16_bf16 v[2:17], v[152:155], v[184:187], v[2:17]
	ds_read_b128 v[152:155], v143
	ds_read_b128 v[184:187], v142 offset:14336
	s_waitcnt lgkmcnt(0)
	v_mfma_f32_32x32x16_bf16 v[114:129], v[152:155], v[156:159], v[114:129]
	v_mfma_f32_32x32x16_bf16 v[82:97], v[152:155], v[160:163], v[82:97]
	v_mfma_f32_32x32x16_bf16 v[50:65], v[152:155], v[180:183], v[50:65]
	v_mfma_f32_32x32x16_bf16 v[18:33], v[152:155], v[184:187], v[18:33]
	ds_read_b128 v[152:155], v143 offset:2048
	s_waitcnt lgkmcnt(0)
	v_mfma_f32_32x32x16_bf16 v[98:113], v[152:155], v[156:159], v[98:113]
	v_mfma_f32_32x32x16_bf16 v[66:81], v[152:155], v[160:163], v[66:81]
	v_mfma_f32_32x32x16_bf16 v[34:49], v[152:155], v[180:183], v[34:49]
	v_mfma_f32_32x32x16_bf16 v[2:17], v[152:155], v[184:187], v[2:17]
	s_setprio 0
	s_cbranch_scc1 .LBB0_108

; DI f32x16 mfma32(bf16x8 a, bf16x8 b, f32x16 c) { return __builtin_amdgcn_mfma_f32_32x32x16_bf16(a, b, c, 0, 0, 0); }
; #define RAW_BARRIER() do { asm volatile("s_waitcnt lgkmcnt(0)" ::: "memory"); __builtin_amdgcn_s_barrier(); } while (0)
; DI void gemm_tile(const Params& p, const GemmJob& j, int mt, int nt, char* smem) {
;     ...
;       const bf16_t* src = j.bblk ? j.Bt + ((size_t)kt * j.bblk + n0 + 16 * ch + rl) * 32 + c8s : j.Bt + (size_t)(n0 + 16 * ch + rl) * j.K + kt * 32 + c8s;
;       __builtin_amdgcn_global_load_lds((gptr_t)src, (lptr_t)(sb + ch * 1024), 16, 0, 0);
;     }
; #pragma unroll
;     for (int q = 0; q < 4; ++q) {
;       const int ch = q * 4 + wid;
;       const bf16_t* src = j.ablk ? j.A + ((size_t)kt * j.ablk + t0 + 16 * ch + rl) * 32 + c8s : j.A + a_rowoff(j, t0 + 16 * ch + rl) + ko + c8s;
;       __builtin_amdgcn_global_load_lds((gptr_t)src, (lptr_t)(sb + 8192 + ch * 1024), 16, 0, 0);
;     }
;   };
;   const int fr = (r >> 2) & 3; const int o0 = (h ^ fr) * 16;
;   __syncthreads();
;   glds(0, 0);
;   if (nk > 1) glds(1, 1);
;   int st = 0, st2 = 2;
;   for (int kt = 0; kt < nk; ++kt) {
;     if (kt + 1 < nk) asm volatile("s_waitcnt vmcnt(6)" ::: "memory"); else asm volatile("s_waitcnt vmcnt(0)" ::: "memory");
;     RAW_BARRIER();
;     if (kt + 2 < nk) glds(kt + 2, st2);
;     const char* sb = smem + st * GSTAGE;
; #pragma unroll
;     for (int ks = 0; ks < 2; ++ks) {
;       const int off = ks ? (o0 ^ 32) : o0;
;       bf16x8 wf[2], xf[4];
; #pragma unroll
;       for (int a = 0; a < 2; ++a) wf[a] = *(const bf16x8*)(sb + (64 * wn + 32 * a + r) * 64 + off);
; #pragma unroll
;       for (int b = 0; b < 4; ++b) xf[b] = *(const bf16x8*)(sb + 8192 + (128 * wt + 32 * b + r) * 64 + off);
; #pragma unroll
;       for (int a = 0; a < 2; ++a)
; #pragma unroll
;         for (int b = 0; b < 4; ++b) acc[a][b] = mfma32(wf[a], xf[b], acc[a][b]);
;     }
;     st = (st == 2) ? 0 : st + 1; st2 = (st2 == 2) ? 0 : st2 + 1;
.LBB0_886:
	s_mul_i32 s10, s54, 0x6000
	s_add_i32 s36, s10, 0
	v_lshl_add_u64 v[142:143], v[132:133], 0, v[0:1]
	s_mov_b64 s[10:11], 0x20000
	s_add_i32 s37, s36, s55
	s_waitcnt vmcnt(6)
	v_lshl_add_u64 v[144:145], v[142:143], 0, s[10:11]
	s_mov_b32 m0, s37
	s_mov_b64 s[10:11], 0x21000
	s_add_i32 s38, s36, s58
	s_waitcnt lgkmcnt(0)
	s_barrier
	global_load_lds_dwordx4 v[144:145], off
	v_lshl_add_u64 v[142:143], v[142:143], 0, s[10:11]
	s_mov_b32 m0, s38
	s_mov_b64 s[10:11], 0x401000
	global_load_lds_dwordx4 v[142:143], off
	v_lshl_add_u64 v[142:143], v[130:131], 0, v[0:1]
	v_lshl_add_u64 v[144:145], v[142:143], 0, s[92:93]
	s_add_i32 m0, s37, 0x2000
	v_lshl_add_u64 v[130:131], v[130:131], 0, s[88:89]
	global_load_lds_dwordx4 v[144:145], off
	v_lshl_add_u64 v[144:145], v[142:143], 0, s[10:11]
	s_add_i32 m0, s38, 0x2000
	s_add_i32 s10, s36, s62
	global_load_lds_dwordx4 v[144:145], off
	v_lshl_add_u64 v[144:145], v[142:143], 0, s[84:85]
	s_add_i32 m0, s10, 0x2000
	s_add_i32 s10, s36, s63
	global_load_lds_dwordx4 v[144:145], off
	v_lshl_add_u64 v[142:143], v[142:143], 0, s[52:53]
	s_add_i32 m0, s10, 0x2000
	s_mul_i32 s10, s6, 0x6000
	global_load_lds_dwordx4 v[142:143], off
	s_add_i32 s10, s10, 0
	v_add_u32_e32 v141, s10, v137
	v_add_u32_e32 v146, v141, v140
	v_add_u32_e32 v141, v141, v139
	ds_read_b128 v[142:145], v146
	ds_read_b128 v[146:149], v146 offset:2048
	ds_read_b128 v[150:153], v141 offset:8192
	ds_read_b128 v[154:157], v141 offset:10240
	ds_read_b128 v[158:161], v141 offset:12288
	ds_read_b128 v[162:165], v141 offset:14336
	s_waitcnt lgkmcnt(0)
	s_setprio 1
	v_mfma_f32_32x32x16_bf16 v[82:97], v[142:145], v[150:153], v[82:97]
	v_add_u32_e32 v141, s10, v138
	s_add_i32 s10, s6, 1
	s_cmp_lg_u32 s6, 2
	s_cselect_b32 s6, s10, 0
	s_add_i32 s10, s54, 1
	s_cmp_lg_u32 s54, 2
	s_cselect_b32 s54, s10, 0
	v_mfma_f32_32x32x16_bf16 v[50:65], v[142:145], v[154:157], v[50:65]
	s_add_i32 s7, s7, -1
	v_lshl_add_u64 v[132:133], v[132:133], 0, s[56:57]
	s_cmp_eq_u32 s7, 0
	v_mfma_f32_32x32x16_bf16 v[18:33], v[142:145], v[158:161], v[18:33]
	v_mfma_f32_32x32x16_bf16 v[2:17], v[142:145], v[162:165], v[2:17]
	v_mfma_f32_32x32x16_bf16 v[114:129], v[146:149], v[150:153], v[114:129]
	v_mfma_f32_32x32x16_bf16 v[98:113], v[146:149], v[154:157], v[98:113]
	v_mfma_f32_32x32x16_bf16 v[66:81], v[146:149], v[158:161], v[66:81]
	v_mfma_f32_32x32x16_bf16 v[34:49], v[146:149], v[162:165], v[34:49]
	v_add_u32_e32 v146, v141, v140
	v_add_u32_e32 v141, v141, v139
	ds_read_b128 v[142:145], v146
	ds_read_b128 v[146:149], v146 offset:2048
	ds_read_b128 v[150:153], v141 offset:8192
	ds_read_b128 v[154:157], v141 offset:10240
	ds_read_b128 v[158:161], v141 offset:12288
	ds_read_b128 v[162:165], v141 offset:14336
	s_waitcnt lgkmcnt(0)
	v_mfma_f32_32x32x16_bf16 v[82:97], v[142:145], v[150:153], v[82:97]
	v_mfma_f32_32x32x16_bf16 v[50:65], v[142:145], v[154:157], v[50:65]
	v_mfma_f32_32x32x16_bf16 v[18:33], v[142:145], v[158:161], v[18:33]
	v_mfma_f32_32x32x16_bf16 v[2:17], v[142:145], v[162:165], v[2:17]
	v_mfma_f32_32x32x16_bf16 v[114:129], v[146:149], v[150:153], v[114:129]
	v_mfma_f32_32x32x16_bf16 v[98:113], v[146:149], v[154:157], v[98:113]
	v_mfma_f32_32x32x16_bf16 v[66:81], v[146:149], v[158:161], v[66:81]
	v_mfma_f32_32x32x16_bf16 v[34:49], v[146:149], v[162:165], v[34:49]
	s_setprio 0
	s_cbranch_scc0 .LBB0_886
	s_mul_i32 s7, s6, 0x6000
	s_add_i32 s10, s7, 0
	v_add_u32_e32 v0, s10, v137
	s_waitcnt vmcnt(6)
	v_add_u32_e32 v141, v0, v140
	s_waitcnt lgkmcnt(0)
	s_barrier
	ds_read_b128 v[130:133], v141
	ds_read_b128 v[142:145], v141 offset:2048
	v_add_u32_e32 v0, v0, v139
	ds_read_b128 v[146:149], v0 offset:8192
	ds_read_b128 v[150:153], v0 offset:10240
	ds_read_b128 v[154:157], v0 offset:12288
	ds_read_b128 v[158:161], v0 offset:14336
	s_waitcnt lgkmcnt(0)
	v_mfma_f32_32x32x16_bf16 v[82:97], v[130:133], v[146:149], v[82:97]
	v_add_u32_e32 v0, s10, v138
	v_add_u32_e32 v141, v0, v140
	v_add_u32_e32 v0, v0, v139
	s_addk_i32 s7, 0x6000
	s_cmp_lg_u32 s6, 2
	s_cselect_b32 s6, s7, 0
	s_add_i32 s6, s6, 0
	v_mfma_f32_32x32x16_bf16 v[114:129], v[142:145], v[146:149], v[114:129]
	v_readlane_b32 s12, v229, 29
	v_readlane_b32 s22, v229, 39
	v_readlane_b32 s23, v229, 40
	v_readlane_b32 s18, v229, 35
	v_readlane_b32 s19, v229, 36
	s_mov_b32 s58, 0
	v_readlane_b32 s13, v229, 30
	v_mfma_f32_32x32x16_bf16 v[50:65], v[130:133], v[150:153], v[50:65]
	v_readlane_b32 s14, v229, 31
	v_readlane_b32 s15, v229, 32
	v_readlane_b32 s16, v229, 33
	v_readlane_b32 s17, v229, 34
	v_readlane_b32 s20, v229, 37
	v_readlane_b32 s21, v229, 38
	v_readlane_b32 s24, v229, 41
	v_mfma_f32_32x32x16_bf16 v[18:33], v[130:133], v[154:157], v[18:33]
	v_readlane_b32 s25, v229, 42
	v_readlane_b32 s26, v229, 43
	v_readlane_b32 s27, v229, 44
	v_mfma_f32_32x32x16_bf16 v[2:17], v[130:133], v[158:161], v[2:17]
	v_mfma_f32_32x32x16_bf16 v[98:113], v[142:145], v[150:153], v[98:113]
	v_mfma_f32_32x32x16_bf16 v[66:81], v[142:145], v[154:157], v[66:81]
	v_mfma_f32_32x32x16_bf16 v[34:49], v[142:145], v[158:161], v[34:49]
	ds_read_b128 v[130:133], v141
	ds_read_b128 v[142:145], v141 offset:2048
	ds_read_b128 v[146:149], v0 offset:8192
	ds_read_b128 v[150:153], v0 offset:10240
	ds_read_b128 v[154:157], v0 offset:12288
	ds_read_b128 v[158:161], v0 offset:14336
	v_add_u32_e32 v0, s6, v137
	s_waitcnt vmcnt(0)
	v_add_u32_e32 v137, v0, v140
	s_waitcnt lgkmcnt(0)
	s_barrier
; DI unsigned pack2(float a, float b) { f32x2 v = {a, b}; bf16x2_t r = __builtin_convertvector(v, bf16x2_t); return __builtin_bit_cast(unsigned, r); }
; DI f32x16 mfma32(bf16x8 a, bf16x8 b, f32x16 c) { return __builtin_amdgcn_mfma_f32_32x32x16_bf16(a, b, c, 0, 0, 0); }
; #define RAW_BARRIER() do { asm volatile("s_waitcnt lgkmcnt(0)" ::: "memory"); __builtin_amdgcn_s_barrier(); } while (0)
; DI void gemm_tile(const Params& p, const GemmJob& j, int mt, int nt, char* smem) {
;     ...
;   for (int kt = 0; kt < nk; ++kt) {
;     if (kt + 1 < nk) asm volatile("s_waitcnt vmcnt(6)" ::: "memory"); else asm volatile("s_waitcnt vmcnt(0)" ::: "memory");
;     RAW_BARRIER();
;     if (kt + 2 < nk) glds(kt + 2, st2);
;     const char* sb = smem + st * GSTAGE;
; #pragma unroll
;     for (int ks = 0; ks < 2; ++ks) {
;       const int off = ks ? (o0 ^ 32) : o0;
;       bf16x8 wf[2], xf[4];
; #pragma unroll
;       for (int a = 0; a < 2; ++a) wf[a] = *(const bf16x8*)(sb + (64 * wn + 32 * a + r) * 64 + off);
; #pragma unroll
;       for (int b = 0; b < 4; ++b) xf[b] = *(const bf16x8*)(sb + 8192 + (128 * wt + 32 * b + r) * 64 + off);
; #pragma unroll
;       for (int a = 0; a < 2; ++a)
; #pragma unroll
;         for (int b = 0; b < 4; ++b) acc[a][b] = mfma32(wf[a], xf[b], acc[a][b]);
;     }
;     st = (st == 2) ? 0 : st + 1; st2 = (st2 == 2) ? 0 : st2 + 1;
;   }
;   __syncthreads();
;     ...
;   } else if (j.epi == E_OUT) {
;     bf16_t* Cs = (bf16_t*)smem;
; #pragma unroll
;     for (int ni = 0; ni < 4; ++ni)
; #pragma unroll
;       for (int mi = 0; mi < 2; ++mi)
; #pragma unroll
;         for (int g = 0; g < 4; ++g)
;           *(u32x2*)(Cs + (128 * wt + 32 * ni + r) * 136 + 64 * wn + 32 * mi + 8 * g + 4 * h) =
;               (u32x2){pack2(acc[mi][ni][4 * g], acc[mi][ni][4 * g + 1]), pack2(acc[mi][ni][4 * g + 2], acc[mi][ni][4 * g + 3])};
;     __syncthreads();
; #pragma unroll 4
	s_waitcnt lgkmcnt(0)
	v_mfma_f32_32x32x16_bf16 v[82:97], v[130:133], v[146:149], v[82:97]
	v_add_u32_e32 v0, v0, v139
	v_mfma_f32_32x32x16_bf16 v[114:129], v[142:145], v[146:149], v[114:129]
	v_mfma_f32_32x32x16_bf16 v[50:65], v[130:133], v[150:153], v[50:65]
	v_mfma_f32_32x32x16_bf16 v[18:33], v[130:133], v[154:157], v[18:33]
	v_mfma_f32_32x32x16_bf16 v[2:17], v[130:133], v[158:161], v[2:17]
	v_mfma_f32_32x32x16_bf16 v[98:113], v[142:145], v[150:153], v[98:113]
	v_mfma_f32_32x32x16_bf16 v[66:81], v[142:145], v[154:157], v[66:81]
	v_mfma_f32_32x32x16_bf16 v[34:49], v[142:145], v[158:161], v[34:49]
	ds_read_b128 v[130:133], v137
	ds_read_b128 v[142:145], v137 offset:2048
	ds_read_b128 v[146:149], v0 offset:8192
	ds_read_b128 v[150:153], v0 offset:10240
	ds_read_b128 v[154:157], v0 offset:12288
	ds_read_b128 v[158:161], v0 offset:14336
	v_add_u32_e32 v0, s6, v138
	v_add_u32_e32 v137, v0, v140
	v_add_u32_e32 v0, v0, v139
	s_and_b32 s6, s31, 0xfffff80
	s_waitcnt lgkmcnt(0)
	v_mfma_f32_32x32x16_bf16 v[82:97], v[130:133], v[146:149], v[82:97]
	v_mfma_f32_32x32x16_bf16 v[114:129], v[142:145], v[146:149], v[114:129]
	v_mfma_f32_32x32x16_bf16 v[50:65], v[130:133], v[150:153], v[50:65]
	v_mfma_f32_32x32x16_bf16 v[18:33], v[130:133], v[154:157], v[18:33]
	v_mfma_f32_32x32x16_bf16 v[2:17], v[130:133], v[158:161], v[2:17]
	v_mfma_f32_32x32x16_bf16 v[98:113], v[142:145], v[150:153], v[98:113]
	v_mfma_f32_32x32x16_bf16 v[66:81], v[142:145], v[154:157], v[66:81]
	v_mfma_f32_32x32x16_bf16 v[34:49], v[142:145], v[158:161], v[34:49]
	ds_read_b128 v[130:133], v137
	ds_read_b128 v[140:143], v137 offset:2048
	ds_read_b128 v[144:147], v0 offset:8192
	ds_read_b128 v[148:151], v0 offset:10240
	ds_read_b128 v[152:155], v0 offset:12288
	ds_read_b128 v[156:159], v0 offset:14336
	v_or_b32_e32 v0, s6, v136
	s_lshl_b32 s6, s33, 7
	s_add_i32 s6, s6, 0
	v_mul_lo_u32 v0, v0, s0
	s_waitcnt vmcnt(0) lgkmcnt(0)
	v_mfma_f32_32x32x16_bf16 v[82:97], v[130:133], v[144:147], v[82:97]
	s_barrier
	v_mfma_f32_32x32x16_bf16 v[114:129], v[140:143], v[144:147], v[114:129]
	s_nop 9
	v_cvt_pk_bf16_f32 v82, v82, v83
	v_cvt_pk_bf16_f32 v83, v84, v85
	v_cvt_pk_bf16_f32 v84, v86, v87
	v_cvt_pk_bf16_f32 v85, v88, v89
	v_mfma_f32_32x32x16_bf16 v[50:65], v[130:133], v[148:151], v[50:65]
	v_mfma_f32_32x32x16_bf16 v[18:33], v[130:133], v[152:155], v[18:33]
	s_nop 10
	v_cvt_pk_bf16_f32 v50, v50, v51
	v_cvt_pk_bf16_f32 v51, v52, v53
	v_cvt_pk_bf16_f32 v52, v54, v55
	v_cvt_pk_bf16_f32 v53, v56, v57
	v_mfma_f32_32x32x16_bf16 v[2:17], v[130:133], v[156:159], v[2:17]
	v_lshlrev_b32_e32 v130, 3, v135
	v_add3_u32 v0, s6, v130, v0
	ds_write2_b64 v0, v[82:83], v[84:85] offset1:2
	v_cvt_pk_bf16_f32 v82, v90, v91
	v_cvt_pk_bf16_f32 v83, v92, v93
	v_cvt_pk_bf16_f32 v84, v94, v95
	v_cvt_pk_bf16_f32 v85, v96, v97
	v_mfma_f32_32x32x16_bf16 v[34:49], v[140:143], v[156:159], v[34:49]
	ds_write2_b64 v0, v[82:83], v[84:85] offset0:4 offset1:6
	v_cvt_pk_bf16_f32 v82, v114, v115
	v_cvt_pk_bf16_f32 v83, v116, v117
	v_cvt_pk_bf16_f32 v84, v118, v119
	v_cvt_pk_bf16_f32 v85, v120, v121
	ds_write2_b64 v0, v[82:83], v[84:85] offset0:8 offset1:10
	v_cvt_pk_bf16_f32 v82, v122, v123
	v_cvt_pk_bf16_f32 v83, v124, v125
	v_cvt_pk_bf16_f32 v84, v126, v127
	v_cvt_pk_bf16_f32 v85, v128, v129
	ds_write2_b64 v0, v[82:83], v[84:85] offset0:12 offset1:14
	v_add_u32_e32 v54, 0x2000, v0
	v_cvt_pk_bf16_f32 v18, v18, v19
	v_cvt_pk_bf16_f32 v19, v20, v21
	v_cvt_pk_bf16_f32 v20, v22, v23
	v_add_u32_e32 v22, 0x4000, v0
	v_cvt_pk_bf16_f32 v2, v2, v3
	v_cvt_pk_bf16_f32 v3, v4, v5
	v_cvt_pk_bf16_f32 v4, v6, v7
	v_cvt_pk_bf16_f32 v5, v8, v9
	v_add_u32_e32 v0, 0x6000, v0
	ds_write2_b64 v0, v[2:3], v[4:5] offset0:192 offset1:194
	v_cvt_pk_bf16_f32 v2, v10, v11
	v_cvt_pk_bf16_f32 v3, v12, v13
	v_cvt_pk_bf16_f32 v4, v14, v15
	v_cvt_pk_bf16_f32 v5, v16, v17
	ds_write2_b64 v0, v[2:3], v[4:5] offset0:196 offset1:198
	v_cvt_pk_bf16_f32 v2, v34, v35
	v_cvt_pk_bf16_f32 v3, v36, v37
	v_cvt_pk_bf16_f32 v4, v38, v39
	v_cvt_pk_bf16_f32 v5, v40, v41
	ds_write2_b64 v0, v[2:3], v[4:5] offset0:200 offset1:202
	v_cvt_pk_bf16_f32 v2, v42, v43
	v_cvt_pk_bf16_f32 v3, v44, v45
	v_cvt_pk_bf16_f32 v4, v46, v47
	v_cvt_pk_bf16_f32 v5, v48, v49
	ds_write2_b64 v0, v[2:3], v[4:5] offset0:204 offset1:206
	v_and_b32_e32 v2, 64, v202
	v_and_b32_e32 v3, 15, v134
	v_add_u32_e32 v2, 64, v2
	v_cmp_eq_u32_e32 vcc, 0, v3
	v_xor_b32_e32 v3, 1, v202
	v_cmp_lt_i32_e64 s[6:7], v3, v2
	v_mfma_f32_32x32x16_bf16 v[66:81], v[140:143], v[152:155], v[66:81]
	v_cvt_pk_bf16_f32 v21, v24, v25
	v_cndmask_b32_e64 v3, v202, v3, s[6:7]
	v_lshlrev_b32_e32 v15, 2, v3
	v_xor_b32_e32 v3, 2, v202
	v_cmp_lt_i32_e64 s[6:7], v3, v2
	v_lshlrev_b32_e32 v0, 3, v134
	v_and_b32_e32 v4, 0x78, v0
	v_cndmask_b32_e64 v3, v202, v3, s[6:7]
	v_lshlrev_b32_e32 v24, 2, v3
	v_xor_b32_e32 v3, 4, v202
	v_cmp_lt_i32_e64 s[6:7], v3, v2
	v_mfma_f32_32x32x16_bf16 v[98:113], v[140:143], v[148:151], v[98:113]
	v_or_b32_sdwa v0, s30, v4 dst_sel:WORD_1 dst_unused:UNUSED_PAD src0_sel:DWORD src1_sel:DWORD
	v_cndmask_b32_e64 v3, v202, v3, s[6:7]
	v_lshlrev_b32_e32 v25, 2, v3
	v_xor_b32_e32 v3, 8, v202
	v_cmp_lt_i32_e64 s[6:7], v3, v2
	v_and_b32_e32 v0, 0x3e00000, v0
	ds_write2_b64 v22, v[18:19], v[20:21] offset0:128 offset1:130
	v_cndmask_b32_e64 v2, v202, v3, s[6:7]
	v_cvt_pk_bf16_f32 v18, v26, v27
	v_cvt_pk_bf16_f32 v19, v28, v29
	v_cvt_pk_bf16_f32 v20, v30, v31
	v_cvt_pk_bf16_f32 v21, v32, v33
	v_lshlrev_b32_e32 v26, 2, v2
	v_lshl_add_u64 v[2:3], s[22:23], 0, v[0:1]
	v_lshlrev_b32_e32 v0, 4, v134
	s_lshl_b32 s6, s30, 2
	ds_write2_b64 v22, v[18:19], v[20:21] offset0:132 offset1:134
	v_cvt_pk_bf16_f32 v18, v66, v67
	v_cvt_pk_bf16_f32 v19, v68, v69
	v_cvt_pk_bf16_f32 v20, v70, v71
	v_cvt_pk_bf16_f32 v21, v72, v73
	v_and_b32_e32 v0, 48, v0
	s_add_u32 s6, s4, s6
	ds_write2_b64 v22, v[18:19], v[20:21] offset0:136 offset1:138
	v_cvt_pk_bf16_f32 v18, v74, v75
	v_cvt_pk_bf16_f32 v19, v76, v77
	v_cvt_pk_bf16_f32 v20, v78, v79
	v_cvt_pk_bf16_f32 v21, v80, v81
	v_lshl_add_u64 v[16:17], v[2:3], 0, v[0:1]
	s_addc_u32 s7, s5, 0
	v_lshlrev_b32_e32 v0, 2, v4
	ds_write2_b64 v54, v[50:51], v[52:53] offset0:64 offset1:66
	v_cvt_pk_bf16_f32 v50, v58, v59
	v_cvt_pk_bf16_f32 v51, v60, v61
	v_cvt_pk_bf16_f32 v52, v62, v63
	v_cvt_pk_bf16_f32 v53, v64, v65
	ds_write2_b64 v22, v[18:19], v[20:21] offset0:140 offset1:142
	v_lshl_add_u64 v[18:19], s[6:7], 0, v[0:1]
	s_and_b64 s[10:11], vcc, s[72:73]
	s_lshl_b32 s6, s29, 2
	ds_write2_b64 v54, v[50:51], v[52:53] offset0:68 offset1:70
	v_cvt_pk_bf16_f32 v50, v98, v99
	v_cvt_pk_bf16_f32 v51, v100, v101
	v_cvt_pk_bf16_f32 v52, v102, v103
	v_cvt_pk_bf16_f32 v53, v104, v105
	s_add_u32 s54, s18, s6
	ds_write2_b64 v54, v[50:51], v[52:53] offset0:72 offset1:74
	v_cvt_pk_bf16_f32 v50, v106, v107
	v_cvt_pk_bf16_f32 v51, v108, v109
	v_cvt_pk_bf16_f32 v52, v110, v111
	v_cvt_pk_bf16_f32 v53, v112, v113
	v_lshl_add_u32 v14, v4, 1, 0
	s_addc_u32 s55, s19, 0
	ds_write2_b64 v54, v[50:51], v[52:53] offset0:76 offset1:78
	s_waitcnt lgkmcnt(0)
	s_barrier
